# NA item prologue: both bias-table loads issued back to back and waited once, instead of a 2-trip load-wait-write loop
# baseline (speedup 1.0000x reference)
; __device__ __forceinline__ void na_item(unsigned char* smem, const bf16_t* U, const float* rpb_l, bf16_t* O, int b, int rp, int hp, float shift) {
;     ...
;     const int rA = 2 * rp, rB = rA + 1;
;     const int rsA = min(max(rA - 4, 0), 24), rsB = min(max(rB - 4, 0), 24), dB = rsB - rsA, nst = dB + 8;
;     const int kcol0 = min(max(16 * qg - 8, 0), 32);
;     const int qc = 16 * qg + fr, cs = min(max(qc - 8, 0), 48);
;     const size_t qrowA = (size_t)b * SEQ + rA * 64 + qc, qrowB = qrowA + 64;
;     bf16x8_t qfA[2], qfB[2];
; #pragma unroll
;     for (int kk = 0; kk < 2; ++kk) { qfA[kk] = *(const bf16x8_t*)(U + qrowA * NINP + OQ + h * 64 + kk * 32 + fq * 8); qfB[kk] = *(const bf16x8_t*)(U + qrowB * NINP + OQ + h * 64 + kk * 32 + fq * 8); }
;     f32x4_t oA[4], oB[4];
; #pragma unroll
;     for (int dg = 0; dg < 4; ++dg) { oA[dg] = (f32x4_t){0.f, 0.f, 0.f, 0.f}; oB[dg] = (f32x4_t){0.f, 0.f, 0.f, 0.f}; }
;     float lA = 0.f, lB = 0.f;
;     const float nsh = -shift;
;     const int srow = tid >> 3, sch = tid & 7;
;     const int crow = (tid & 255) >> 3, cisv = tid >> 8;
;     const size_t latbase = ((size_t)b * SEQ + (size_t)rsA * 64 + srow) * NINP + sch * 8;
;     const size_t ctxbase = ((size_t)NLAT + b * CTXL + crow) * NINP + (cisv ? OV : OKK) + sch * 8;
;     u32x4_t rg[6];
;     ...
;     NA_LOAD(0);
;     __syncthreads();
;     for (int i2 = tid; i2 < 2 * 15 * 32; i2 += 512) { const int e = i2 / 480, rr = (i2 % 480) >> 5, x = i2 & 31;
;         bias[i2] = x < 31 ? rpb_l[((2 * hp + e) * 15 + rr) * 31 + x] * LOG2E : 0.f; }
.LBB0_838:
	s_andn2_b64 vcc, exec, s[2:3]
	s_cbranch_vccnz .LBB0_821
	s_lshr_b32 s2, s26, 4
	s_add_i32 s2, s2, s12
	s_and_b32 s3, s13, 15
	s_mul_hi_u32 s5, s2, 0xaaaaaaab
	s_lshr_b32 s16, s5, 1
	s_lshl_b32 s26, s3, 1
	s_mul_i32 s5, s16, 3
	v_mov_b32_e32 v62, v253
	v_sub_u32_e64 v1, s26, 4 clamp
	s_sub_i32 s5, s2, s5
	v_readfirstlane_b32 s2, v1
	v_lshrrev_b32_e32 v1, 2, v62
	v_and_b32_e32 v61, 15, v62
	s_min_u32 s27, s2, 24
	s_waitcnt vmcnt(6)
	v_and_b32_e32 v51, 48, v1
	s_lshl_b32 s17, s16, 11
	s_lshl_b32 s2, s3, 7
	v_ashrrev_i32_e32 v63, 8, v62
	s_lshl_b32 s13, s5, 1
	v_or_b32_e32 v60, v51, v61
	s_or_b32 s2, s17, s2
	v_or_b32_e32 v1, s2, v60
	v_mov_b64_e32 v[2:3], s[68:69]
	v_add_lshl_u32 v106, v63, s13, 6
	v_bfe_u32 v64, v62, 4, 2
	v_mad_u64_u32 v[4:5], s[2:3], v1, s90, v[2:3]
	v_ashrrev_i32_e32 v107, 31, v106
	v_lshl_add_u64 v[4:5], v[106:107], 1, v[4:5]
	v_lshlrev_b32_e32 v108, 4, v64
	v_mov_b32_e32 v109, v0
	v_lshl_add_u64 v[4:5], v[4:5], 0, v[108:109]
	s_mov_b32 s2, 0x48000
	v_add_co_u32_e32 v8, vcc, s2, v4
	v_bfe_u32 v52, v62, 3, 5
	s_lshl_b32 s2, s27, 6
	v_lshl_add_u64 v[6:7], v[4:5], 0, s[34:35]
	v_addc_co_u32_e32 v9, vcc, 0, v5, vcc
	global_load_dwordx4 v[14:17], v[4:5], off
	global_load_dwordx4 v[18:21], v[4:5], off offset:64
	global_load_dwordx4 v[22:25], v[8:9], off
	global_load_dwordx4 v[26:29], v[6:7], off offset:64
	v_ashrrev_i32_e32 v46, 3, v62
	s_or_b32 s54, s2, s17
	v_lshl_or_b32 v5, s16, 8, v52
	s_movk_i32 s2, 0x900
	v_ashrrev_i32_e32 v47, 31, v46
	s_waitcnt vmcnt(9)
	v_mul_lo_u32 v54, v5, s2
	s_movk_i32 s2, 0x100
	v_lshl_add_u64 v[48:49], v[46:47], 0, s[54:55]
	v_cmp_gt_u32_e32 vcc, s2, v62
	v_and_b32_e32 v4, 7, v62
	v_mad_u64_u32 v[2:3], s[2:3], v48, s90, v[2:3]
	v_cndmask_b32_e32 v5, v211, v252, vcc
	v_mad_i32_i24 v3, v49, s90, v3
	v_lshlrev_b32_e32 v110, 4, v4
	v_mov_b32_e32 v111, v0
	v_lshlrev_b32_e32 v56, 1, v5
	v_mov_b32_e32 v57, v0
	v_lshl_add_u64 v[42:43], v[2:3], 0, v[110:111]
	v_lshl_add_u64 v[2:3], s[68:69], 0, v[56:57]
	v_mov_b32_e32 v55, v0
	v_lshl_add_u64 v[2:3], v[54:55], 1, v[2:3]
	v_lshl_add_u64 v[2:3], v[2:3], 0, v[110:111]
	s_mov_b64 s[2:3], 0x9000000
	v_lshl_add_u64 v[44:45], v[2:3], 0, s[2:3]
	s_lshl_b32 s54, s5, 8
	v_lshl_add_u64 v[6:7], v[42:43], 0, s[54:55]
	v_lshl_add_u64 v[10:11], v[44:45], 0, s[54:55]
	global_load_dwordx4 v[30:33], v[6:7], off offset:768
	global_load_dwordx4 v[2:5], v[6:7], off offset:896
	global_load_dwordx4 v[38:41], v[6:7], off offset:1536
	s_nop 0
	global_load_dwordx4 v[6:9], v[6:7], off offset:1664
	s_nop 0
	global_load_dwordx4 v[34:37], v[10:11], off
	s_nop 0
	global_load_dwordx4 v[10:13], v[10:11], off offset:128
	v_sub_u32_e64 v47, s26, 3 clamp
	s_movk_i32 s2, 0x3c0
	v_readfirstlane_b32 s28, v47
	v_cmp_gt_i32_e64 s[38:39], s2, v62
	s_barrier
	s_mov_b64 s[2:3], exec
	v_and_b32_e32 v50, 31, v62
	v_cmp_ne_u32_e64 s[38:39], 31, v50
	v_lshl_add_u32 v47, v62, 2, s4
	v_mov_b32_e32 v57, 0
	v_mov_b32_e32 v65, 0
	s_movk_i32 s18, 0x1c0
	v_cmp_gt_u32_e64 s[20:21], s18, v62
	s_and_b64 s[16:17], s[20:21], s[38:39]
	v_add_u32_e32 v85, 0x200, v62
	s_mov_b32 s18, 0x88888889
	s_and_b64 exec, s[2:3], s[38:39]
	v_mul_hi_i32 v84, v62, s18
	v_add_u32_e32 v84, v84, v62
	v_lshrrev_b32_e32 v80, 31, v84
	v_ashrrev_i32_e32 v84, 8, v84
	v_add_u32_e32 v84, v84, v80
	v_mul_i32_i24_e32 v80, 0x1e0, v84
	v_sub_u32_e32 v80, v62, v80
	v_ashrrev_i32_e32 v80, 5, v80
	v_add_u32_e32 v84, s13, v84
	v_mad_u32_u24 v80, v84, 15, v80
	v_mad_u32_u24 v80, v80, 31, v50
	v_ashrrev_i32_e32 v81, 31, v80
	v_lshl_add_u64 v[80:81], v[80:81], 2, s[42:43]
	global_load_dword v57, v[80:81], off
	s_and_b64 exec, s[2:3], s[16:17]
	v_mul_hi_i32 v86, v85, s18
	v_add_u32_e32 v86, v86, v85
	v_lshrrev_b32_e32 v82, 31, v86
	v_ashrrev_i32_e32 v86, 8, v86
	v_add_u32_e32 v86, v86, v82
	v_mul_i32_i24_e32 v82, 0x1e0, v86
	v_sub_u32_e32 v82, v85, v82
	v_ashrrev_i32_e32 v82, 5, v82
	v_add_u32_e32 v86, s13, v86
	v_mad_u32_u24 v82, v86, 15, v82
	v_mad_u32_u24 v82, v82, 31, v50
	v_ashrrev_i32_e32 v83, 31, v82
	v_lshl_add_u64 v[82:83], v[82:83], 2, s[42:43]
	global_load_dword v65, v[82:83], off
	s_mov_b64 exec, s[2:3]
	s_waitcnt vmcnt(0)
	v_mul_f32_e32 v57, 0x3fb8aa3b, v57
	v_mul_f32_e32 v65, 0x3fb8aa3b, v65
	ds_write_b32 v47, v57
	s_and_b64 exec, s[2:3], s[20:21]
	ds_write_b32 v47, v65 offset:2048
	s_mov_b64 exec, s[2:3]
